# SSD prompt chunk loop: fragment reads of the three MFMA blocks issued together with counted lgkmcnt (21 -> 4 serial LDS round trips per chunk)
# speedup vs baseline: 1.0034x; 1.0000x over previous
.LBB0_269:
	s_waitcnt lgkmcnt(0)
	s_barrier
	v_mov_b32_e32 v38, 0
	v_mov_b32_e32 v40, 0
	v_mov_b32_e32 v41, 0
	v_mov_b32_e32 v42, 0
	v_mov_b32_e32 v43, 0
	s_and_saveexec_b64 s[84:85], s[22:23]
	s_cbranch_execz .LBB0_271
	ds_read_b128 v[40:43], v90
	ds_read_b128 v[166:169], v104 offset:17408
	ds_read_b128 v[208:211], v90 offset:64
	ds_read_b128 v[188:191], v104 offset:17472
	ds_read_b128 v[218:221], v90 offset:128
	ds_read_b128 v[212:215], v104 offset:17536
	ds_read_b128 v[226:229], v90 offset:192
	ds_read_b128 v[222:225], v104 offset:17600
	s_waitcnt lgkmcnt(6)
	v_mfma_f32_16x16x32_bf16 v[40:43], v[40:43], v[166:169], 0
	s_waitcnt lgkmcnt(4)
	v_mfma_f32_16x16x32_bf16 v[40:43], v[208:211], v[188:191], v[40:43]
	s_waitcnt lgkmcnt(2)
	v_mfma_f32_16x16x32_bf16 v[40:43], v[218:221], v[212:215], v[40:43]
	s_waitcnt lgkmcnt(0)
	v_mfma_f32_16x16x32_bf16 v[40:43], v[226:229], v[222:225], v[40:43]
.LBB0_271:
	s_or_b64 exec, exec, s[84:85]
	ds_read_b32 v39, v126
	ds_read_b32 v87, v127
	ds_read_b32 v44, v105
	ds_read_b32 v85, v107
	s_waitcnt lgkmcnt(1)
	v_sub_f32_e32 v45, v44, v39
	v_mul_f32_e32 v45, 0x3fb8aa3b, v45
	v_exp_f32_e32 v45, v45
	s_nop 0
	v_mul_f32_e32 v40, v40, v45
	ds_read_b32 v45, v106
	v_mul_f32_e32 v40, v87, v40
	v_cndmask_b32_e64 v40, v40, 0, s[26:27]
	v_cvt_pk_bf16_f32 v40, v40, v40
	ds_write_b16 v128, v40
	s_waitcnt lgkmcnt(1)
	v_sub_f32_e32 v40, v45, v39
	v_mul_f32_e32 v40, 0x3fb8aa3b, v40
	v_exp_f32_e32 v40, v40
	s_nop 0
	v_mul_f32_e32 v40, v41, v40
	v_mul_f32_e32 v40, v87, v40
	v_cndmask_b32_e64 v40, v40, 0, s[28:29]
	v_cvt_pk_bf16_f32 v40, v40, v40
	ds_write_b16 v129, v40
	v_sub_f32_e32 v40, v85, v39
	v_mul_f32_e32 v40, 0x3fb8aa3b, v40
	v_exp_f32_e32 v40, v40
	v_mov_b32_e32 v41, 0
	v_mul_f32_e32 v40, v42, v40
	ds_read_b32 v42, v108
	v_mul_f32_e32 v40, v87, v40
	v_cndmask_b32_e64 v40, v40, 0, s[30:31]
	v_cvt_pk_bf16_f32 v40, v40, v40
	ds_write_b16 v130, v40
	s_waitcnt lgkmcnt(1)
	v_sub_f32_e32 v39, v42, v39
	v_mul_f32_e32 v39, 0x3fb8aa3b, v39
	v_exp_f32_e32 v39, v39
	v_mov_b32_e32 v40, 0
	v_mul_f32_e32 v39, v43, v39
	v_mul_f32_e32 v39, v87, v39
	v_cndmask_b32_e64 v39, v39, 0, s[34:35]
	v_cvt_pk_bf16_f32 v39, v39, v39
	ds_write_b16 v131, v39
	v_mov_b32_e32 v39, 0
	s_and_saveexec_b64 s[84:85], s[24:25]
	s_cbranch_execz .LBB0_273
	ds_read_b128 v[38:41], v90
	ds_read_b128 v[166:169], v109 offset:17408
	ds_read_b128 v[208:211], v90 offset:64
	ds_read_b128 v[188:191], v109 offset:17472
	ds_read_b128 v[218:221], v90 offset:128
	ds_read_b128 v[212:215], v109 offset:17536
	ds_read_b128 v[226:229], v90 offset:192
	ds_read_b128 v[222:225], v109 offset:17600
	s_waitcnt lgkmcnt(6)
	v_mfma_f32_16x16x32_bf16 v[38:41], v[38:41], v[166:169], 0
	s_waitcnt lgkmcnt(4)
	v_mfma_f32_16x16x32_bf16 v[38:41], v[208:211], v[188:191], v[38:41]
	s_waitcnt lgkmcnt(2)
	v_mfma_f32_16x16x32_bf16 v[38:41], v[218:221], v[212:215], v[38:41]
	s_waitcnt lgkmcnt(0)
	v_mfma_f32_16x16x32_bf16 v[38:41], v[226:229], v[222:225], v[38:41]
.LBB0_273:
	s_or_b64 exec, exec, s[84:85]
	ds_read_b32 v43, v132
	ds_read_b32 v87, v133
	s_waitcnt vmcnt(20)
	v_lshlrev_b32_e32 v84, 16, v84
	s_mov_b32 s0, 0x25f92000
	s_mov_b64 s[84:85], 0x800
	s_waitcnt lgkmcnt(1)
	v_sub_f32_e32 v44, v44, v43
	v_mul_f32_e32 v44, 0x3fb8aa3b, v44
	v_exp_f32_e32 v44, v44
	s_nop 0
	v_mul_f32_e32 v38, v38, v44
	s_waitcnt lgkmcnt(0)
	v_mul_f32_e32 v38, v87, v38
	v_cndmask_b32_e64 v38, v38, 0, s[36:37]
	v_cvt_pk_bf16_f32 v38, v38, v38
	ds_write_b16 v128, v38 offset:32
	v_sub_f32_e32 v38, v45, v43
	v_mul_f32_e32 v38, 0x3fb8aa3b, v38
	v_exp_f32_e32 v38, v38
	s_nop 0
	v_mul_f32_e32 v38, v39, v38
	v_mul_f32_e32 v38, v87, v38
	v_cndmask_b32_e64 v38, v38, 0, s[38:39]
	v_cvt_pk_bf16_f32 v38, v38, v38
	ds_write_b16 v129, v38 offset:32
	v_sub_f32_e32 v38, v85, v43
	v_mul_f32_e32 v38, 0x3fb8aa3b, v38
	v_exp_f32_e32 v38, v38
	s_nop 0
	v_mul_f32_e32 v38, v40, v38
	v_mul_f32_e32 v38, v87, v38
	v_cndmask_b32_e64 v38, v38, 0, s[40:41]
	v_cvt_pk_bf16_f32 v38, v38, v38
	ds_write_b16 v130, v38 offset:32
	v_sub_f32_e32 v38, v42, v43
	v_mul_f32_e32 v38, 0x3fb8aa3b, v38
	v_exp_f32_e32 v38, v38
	s_nop 0
	v_mul_f32_e32 v38, v41, v38
	v_mul_f32_e32 v38, v87, v38
	v_cndmask_b32_e64 v38, v38, 0, s[42:43]
	v_cvt_pk_bf16_f32 v38, v38, v38
	ds_write_b16 v131, v38 offset:32
	s_waitcnt lgkmcnt(0)
	s_barrier
	ds_read_b128 v[38:41], v90
	ds_read_b128 v[42:45], v134
	ds_read_b128 v[166:169], v110
	ds_read_b128 v[188:191], v90 offset:64
	ds_read_b128 v[208:211], v134 offset:64
	ds_read_b128 v[212:215], v110 offset:64
	ds_read_b128 v[218:221], v90 offset:128
	ds_read_b128 v[222:225], v134 offset:128
	ds_read_b128 v[226:229], v110 offset:128
	ds_read_b128 v[230:233], v90 offset:192
	ds_read_b128 v[234:237], v134 offset:192
	ds_read_b128 v[238:241], v110 offset:192
	s_waitcnt lgkmcnt(10)
	v_mfma_f32_16x16x32_bf16 v[42:45], v[38:41], v[42:45], 0
	s_waitcnt lgkmcnt(9)
	v_mfma_f32_16x16x32_bf16 v[38:41], v[38:41], v[166:169], 0
	s_waitcnt lgkmcnt(7)
	v_mfma_f32_16x16x32_bf16 v[42:45], v[188:191], v[208:211], v[42:45]
	s_waitcnt lgkmcnt(6)
	v_mfma_f32_16x16x32_bf16 v[38:41], v[188:191], v[212:215], v[38:41]
	s_waitcnt lgkmcnt(4)
	v_mfma_f32_16x16x32_bf16 v[42:45], v[218:221], v[222:225], v[42:45]
	s_waitcnt lgkmcnt(3)
	v_mfma_f32_16x16x32_bf16 v[38:41], v[218:221], v[226:229], v[38:41]
	s_waitcnt lgkmcnt(1)
	v_mfma_f32_16x16x32_bf16 v[42:45], v[230:233], v[234:237], v[42:45]
	s_waitcnt lgkmcnt(0)
	v_mfma_f32_16x16x32_bf16 v[38:41], v[230:233], v[238:241], v[38:41]
	ds_read2_b32 v[166:167], v105 offset1:1
	ds_read2_b32 v[242:243], v107 offset1:1
	ds_read_b128 v[208:211], v91
	ds_read_b128 v[188:191], v135 offset:53248
	ds_read_b128 v[212:215], v111 offset:53248
	ds_read_b128 v[218:221], v91 offset:64
	ds_read_b128 v[222:225], v136 offset:53248
	ds_read_b128 v[226:229], v112 offset:53248
	s_waitcnt lgkmcnt(6)
	v_mul_f32_e32 v85, 0x3fb8aa3b, v166
	v_exp_f32_e32 v170, v85
	v_mul_f32_e32 v85, 0x3fb8aa3b, v167
	v_exp_f32_e32 v171, v85
	v_mul_f32_e32 v85, 0x3fb8aa3b, v242
	v_exp_f32_e32 v192, v85
	v_mul_f32_e32 v85, 0x3fb8aa3b, v243
	v_exp_f32_e32 v193, v85
	s_nop 0
	ds_read_u16 v85, v137 offset:53248
	ds_read_u16 v194, v138 offset:53248
	ds_read_u16 v195, v139 offset:53248
	ds_read_u16 v196, v140 offset:53248
	ds_read_u16 v197, v113 offset:53248
	ds_read_u16 v198, v114 offset:53248
	ds_read_u16 v199, v115 offset:53248
	ds_read_u16 v200, v116 offset:53248
	v_pk_mul_f32 v[42:43], v[42:43], v[170:171]
	v_pk_mul_f32 v[38:39], v[38:39], v[170:171]
	v_pk_mul_f32 v[44:45], v[44:45], v[192:193]
	v_pk_mul_f32 v[40:41], v[40:41], v[192:193]
	s_waitcnt lgkmcnt(12)
	v_mfma_f32_16x16x32_bf16 v[42:45], v[208:211], v[188:191], v[42:45]
	s_waitcnt lgkmcnt(11)
	v_mfma_f32_16x16x32_bf16 v[38:41], v[208:211], v[212:215], v[38:41]
	s_waitcnt lgkmcnt(9)
	v_mfma_f32_16x16x32_bf16 v[42:45], v[218:221], v[222:225], v[42:45]
	s_waitcnt lgkmcnt(8)
	v_mfma_f32_16x16x32_bf16 v[38:41], v[218:221], v[226:229], v[38:41]
	s_waitcnt lgkmcnt(0)
	v_lshlrev_b32_e32 v85, 16, v85
	v_lshl_add_u64 v[166:167], s[50:51], 0, v[72:73]
	s_nop 3
	v_fma_f32 v42, v51, v85, v42
	v_mul_f32_e32 v85, 0xbfb8aa3b, v84
	v_exp_f32_e32 v85, v85
	v_add_co_u32_e32 v168, vcc, s0, v166
	s_mov_b64 s[0:1], 0x1000
	v_add_f32_e32 v85, 1.0, v85
	v_rcp_f32_e32 v85, v85
	v_addc_co_u32_e32 v169, vcc, 0, v167, vcc
	v_mul_f32_e32 v84, v85, v84
	v_mul_f32_e32 v144, v84, v42
	v_cvt_pk_bf16_f32 v42, v144, v144
	global_store_short v[168:169], v42, off offset:-4096
	v_mov_b32_e32 v42, v194
	v_lshl_add_u64 v[84:85], v[82:83], 0, s[56:57]
	s_waitcnt lgkmcnt(0)
	v_lshlrev_b32_e32 v42, 16, v42
	v_fma_f32 v42, v51, v42, v43
	s_waitcnt vmcnt(20)
	v_lshlrev_b32_e32 v43, 16, v86
	v_mul_f32_e32 v86, 0xbfb8aa3b, v43
	v_exp_f32_e32 v86, v86
	s_nop 0
	v_add_f32_e32 v86, 1.0, v86
	v_rcp_f32_e32 v86, v86
	s_nop 0
	v_mul_f32_e32 v43, v86, v43
	v_mul_f32_e32 v165, v43, v42
	v_cvt_pk_bf16_f32 v42, v165, v165
	global_store_short v[168:169], v42, off
	v_mov_b32_e32 v42, v195
	s_waitcnt vmcnt(20)
	v_lshlrev_b32_e32 v43, 16, v164
	v_lshl_add_u64 v[86:87], v[84:85], 0, s[84:85]
	v_or_b32_e32 v86, v86, v66
	s_waitcnt lgkmcnt(0)
	v_lshlrev_b32_e32 v42, 16, v42
	v_fma_f32 v42, v51, v42, v44
	v_mul_f32_e32 v44, 0xbfb8aa3b, v43
	v_exp_f32_e32 v44, v44
	s_nop 0
	v_add_f32_e32 v44, 1.0, v44
	v_rcp_f32_e32 v44, v44
	s_nop 0
	v_mul_f32_e32 v43, v44, v43
	v_mul_f32_e32 v164, v43, v42
	v_lshl_add_u64 v[42:43], v[84:85], 0, s[0:1]
	s_mov_b32 s0, 0x25f94000
	v_add_co_u32_e32 v166, vcc, s0, v166
	v_cvt_pk_bf16_f32 v44, v164, v164
	s_mov_b64 s[0:1], 0x1800
	s_nop 0
	v_addc_co_u32_e32 v167, vcc, 0, v167, vcc
	global_store_short v[166:167], v44, off offset:-4096
	v_mov_b32_e32 v44, v196
	v_or_b32_e32 v42, v42, v66
	v_lshl_add_u64 v[42:43], v[42:43], 1, s[74:75]
	s_waitcnt lgkmcnt(0)
	v_lshlrev_b32_e32 v44, 16, v44
	v_fmac_f32_e32 v45, v51, v44
	s_waitcnt vmcnt(20)
	v_lshlrev_b32_e32 v44, 16, v163
	v_mul_f32_e32 v145, 0xbfb8aa3b, v44
	v_exp_f32_e32 v145, v145
	s_nop 0
	v_add_f32_e32 v145, 1.0, v145
	v_rcp_f32_e32 v145, v145
	s_nop 0
	v_mul_f32_e32 v44, v145, v44
	v_mul_f32_e32 v163, v44, v45
	v_cvt_pk_bf16_f32 v145, v163, v163
	global_store_short v[166:167], v145, off
	v_mov_b32_e32 v145, v197
	v_lshl_add_u64 v[44:45], v[84:85], 0, s[0:1]
	v_or_b32_e32 v84, v84, v66
	v_lshl_add_u64 v[84:85], v[84:85], 1, s[74:75]
	v_or_b32_e32 v44, v44, v66
	s_waitcnt lgkmcnt(0)
	v_lshlrev_b32_e32 v145, 16, v145
	v_fma_f32 v38, v51, v145, v38
	s_waitcnt vmcnt(20)
	v_lshlrev_b32_e32 v145, 16, v160
	v_mul_f32_e32 v146, 0xbfb8aa3b, v145
	v_exp_f32_e32 v146, v146
	s_nop 0
	v_add_f32_e32 v146, 1.0, v146
	v_rcp_f32_e32 v146, v146
	s_nop 0
	v_mul_f32_e32 v145, v146, v145
	v_mul_f32_e32 v38, v145, v38
	v_cvt_pk_bf16_f32 v145, v38, v38
	global_store_short v[84:85], v145, off
	v_mul_f32_e32 v145, v38, v38
	v_mov_b32_e32 v38, v198
	v_fmac_f32_e32 v145, v144, v144
	s_waitcnt lgkmcnt(0)
	v_lshlrev_b32_e32 v38, 16, v38
	v_fma_f32 v38, v51, v38, v39
	s_waitcnt vmcnt(18)
	v_lshlrev_b32_e32 v39, 16, v154
	v_mul_f32_e32 v84, 0xbfb8aa3b, v39
	v_exp_f32_e32 v84, v84
	s_nop 0
	v_add_f32_e32 v84, 1.0, v84
	v_rcp_f32_e32 v84, v84
	s_nop 0
	v_mul_f32_e32 v39, v84, v39
	v_mul_f32_e32 v38, v39, v38
	v_cvt_pk_bf16_f32 v39, v38, v38
	v_lshl_add_u64 v[84:85], v[86:87], 1, s[74:75]
	global_store_short v[84:85], v39, off
	v_mov_b32_e32 v39, v199
	s_waitcnt lgkmcnt(0)
	v_lshlrev_b32_e32 v39, 16, v39
	v_fma_f32 v39, v51, v39, v40
	v_lshlrev_b32_e32 v40, 16, v153
	v_mul_f32_e32 v84, 0xbfb8aa3b, v40
	v_exp_f32_e32 v84, v84
	s_nop 0
	v_add_f32_e32 v84, 1.0, v84
	v_rcp_f32_e32 v84, v84
	s_nop 0
	v_mul_f32_e32 v40, v84, v40
	v_mul_f32_e32 v39, v40, v39
	v_cvt_pk_bf16_f32 v40, v39, v39
	global_store_short v[42:43], v40, off
	v_mov_b32_e32 v40, v200
	s_waitcnt lgkmcnt(0)
	v_lshlrev_b32_e32 v40, 16, v40
	v_fmac_f32_e32 v41, v51, v40
	v_lshlrev_b32_e32 v40, 16, v141
	v_mul_f32_e32 v42, 0xbfb8aa3b, v40
	v_exp_f32_e32 v42, v42
	s_nop 0
	v_add_f32_e32 v42, 1.0, v42
	v_rcp_f32_e32 v42, v42
	s_nop 0
	v_mul_f32_e32 v40, v42, v40
	v_lshl_add_u64 v[42:43], v[44:45], 1, s[74:75]
	v_mul_f32_e32 v40, v40, v41
	v_cvt_pk_bf16_f32 v41, v40, v40
	global_store_short v[42:43], v41, off
	v_and_b32_e32 v42, 64, v177
	v_xor_b32_e32 v41, 1, v177
	v_add_u32_e32 v44, 64, v42
	v_cmp_lt_i32_e32 vcc, v41, v44
	v_xor_b32_e32 v42, 2, v177
	v_xor_b32_e32 v43, 4, v177
	v_cndmask_b32_e32 v41, v177, v41, vcc
	v_cmp_lt_i32_e32 vcc, v42, v44
	v_xor_b32_e32 v45, 8, v177
	v_lshlrev_b32_e32 v41, 2, v41
	v_cndmask_b32_e32 v42, v177, v42, vcc
	v_cmp_lt_i32_e32 vcc, v43, v44
	v_lshlrev_b32_e32 v42, 2, v42
	s_nop 0
	v_cndmask_b32_e32 v43, v177, v43, vcc
	v_cmp_lt_i32_e32 vcc, v45, v44
	v_lshlrev_b32_e32 v43, 2, v43
	s_nop 0
	v_cndmask_b32_e32 v44, v177, v45, vcc
	v_lshlrev_b32_e32 v44, 2, v44
	v_mul_f32_e32 v201, v38, v38
	v_fmac_f32_e32 v201, v165, v165
	v_mul_f32_e32 v202, v39, v39
	v_fmac_f32_e32 v202, v164, v164
	v_mul_f32_e32 v203, v40, v40
	v_fmac_f32_e32 v203, v163, v163
	ds_bpermute_b32 v204, v41, v145
	ds_bpermute_b32 v205, v41, v201
	ds_bpermute_b32 v206, v41, v202
	ds_bpermute_b32 v207, v41, v203
	s_waitcnt lgkmcnt(0)
	v_add_f32_e32 v145, v145, v204
	v_add_f32_e32 v201, v201, v205
	v_add_f32_e32 v202, v202, v206
	v_add_f32_e32 v203, v203, v207
	ds_bpermute_b32 v204, v42, v145
	ds_bpermute_b32 v205, v42, v201
	ds_bpermute_b32 v206, v42, v202
	ds_bpermute_b32 v207, v42, v203
	s_waitcnt lgkmcnt(0)
	v_add_f32_e32 v145, v145, v204
	v_add_f32_e32 v201, v201, v205
	v_add_f32_e32 v202, v202, v206
	v_add_f32_e32 v203, v203, v207
	ds_bpermute_b32 v204, v43, v145
	ds_bpermute_b32 v205, v43, v201
	ds_bpermute_b32 v206, v43, v202
	ds_bpermute_b32 v207, v43, v203
	s_waitcnt lgkmcnt(0)
	v_add_f32_e32 v145, v145, v204
	v_add_f32_e32 v201, v201, v205
	v_add_f32_e32 v202, v202, v206
	v_add_f32_e32 v203, v203, v207
	ds_bpermute_b32 v204, v44, v145
	ds_bpermute_b32 v205, v44, v201
	ds_bpermute_b32 v206, v44, v202
	ds_bpermute_b32 v207, v44, v203
	s_waitcnt lgkmcnt(0)
	v_add_f32_e32 v145, v145, v204
	v_add_f32_e32 v201, v201, v205
	v_add_f32_e32 v202, v202, v206
	v_add_f32_e32 v203, v203, v207
	s_and_saveexec_b64 s[84:85], s[8:9]
	s_cbranch_execz .LBB0_259
	ds_write_b32 v117, v145
	ds_write_b32 v117, v201 offset:4
	ds_write_b32 v117, v202 offset:8
	ds_write_b32 v117, v203 offset:12
	s_branch .LBB0_259
